# S5 scan parallelised over 4 waves (16-step local scans + LDS exchange + A^k correction, f32), one extra barrier per step
# speedup vs baseline: 1.0122x; 1.0037x over previous
; __device__ __forceinline__ int opaque_tid() { int t = threadIdx.x; asm volatile("" : "+v"(t)); return t; }
; #define BAR_LDS() asm volatile("s_waitcnt lgkmcnt(0)\n\ts_barrier" ::: "memory")
; __device__ __forceinline__ void s5_unit(const Args& A, char* lds, int b, int g) {
;     const int tid = opaque_tid(), lane = tid & 63, wave = __builtin_amdgcn_readfirstlane(tid >> 6); const int fr = lane & 15, fq = lane >> 4, r32 = lane & 31, hi = lane >> 5;
;     const bf16* P1 = (const bf16*)(A.ws + WS_BIG); bf16* YD = (bf16*)A.out;
;     const unsigned char* pg = A.ws + WS_S5P + (size_t)g * S5P_STRIDE; const bf16* BbT = (const bf16*)pg; const bf16* Cm = (const bf16*)(pg + 4096); const float* ari = (const float*)(pg + 8192);
;     const int ttile = wave >> 2, ntile = wave & 3;
;     const bf16x8 bfrag = *(const bf16x8*)(BbT + (ntile * 32 + r32) * 16 + 8 * hi);
;     bf16x8 cfrag[4];
; #pragma unroll
;     for (int ks = 0; ks < 4; ++ks) cfrag[ks] = *(const bf16x8*)(Cm + fr * 128 + ks * 32 + 8 * fq);
;     const float ar = ari[lane], ai = ari[64 + lane]; float sr = 0.f, si = 0.f;
;     const float dskip = A.in[I_ODSKIP][g * 16 + fr];
;     const size_t rb0 = (size_t)b * SEQL; const bf16* pU = P1 + (rb0 + ttile * 32 + r32) * LD1 + C1_U + g * 16 + 8 * hi;
;     bf16x8 un = *(const bf16x8*)pU;
;     BAR_LDS();
.LBB0_1346:
	s_and_b32 s8, s42, 31
	v_mov_b32_e32 v14, v220
	s_lshl_b32 s44, s8, 5
	s_and_b32 s8, s43, 31
	s_ashr_i32 s16, s43, 5
	v_readfirstlane_b32 s20, v14
	s_ashr_i32 s45, s20, 6
	s_mul_i32 s17, s8, 0x2200
	v_and_b32_e32 v48, 15, v14
	s_add_u32 s18, s4, s17
	s_addc_u32 s19, s5, 0
	v_lshlrev_b32_e32 v2, 8, v48
	v_mov_b32_e32 v3, v41
	v_and_b32_e32 v45, 31, v14
	v_lshl_add_u64 v[2:3], s[18:19], 0, v[2:3]
	v_and_b32_e32 v4, 48, v14
	v_mov_b32_e32 v5, v41
	v_and_b32_e32 v15, 63, v14
	s_and_b32 s21, s45, 3
	v_lshlrev_b32_e32 v0, 5, v45
	v_lshl_add_u64 v[2:3], v[2:3], 0, v[4:5]
	v_bfe_u32 v46, v14, 5, 1
	v_lshl_or_b32 v40, s21, 10, v0
	v_lshl_add_u64 v[6:7], v[2:3], 0, s[10:11]
	v_add_co_u32_e32 v2, vcc, s26, v2
	v_lshlrev_b32_e32 v8, 2, v15
	v_mov_b32_e32 v9, v41
	v_lshl_add_u64 v[0:1], s[18:19], 0, v[40:41]
	v_lshlrev_b32_e32 v40, 4, v46
	v_addc_co_u32_e32 v3, vcc, 0, v3, vcc
	v_lshl_add_u64 v[10:11], s[18:19], 0, v[8:9]
	s_ashr_i32 s18, s20, 3
	v_lshl_add_u64 v[0:1], v[0:1], 0, v[40:41]
	v_lshl_add_u64 v[12:13], v[10:11], 0, s[12:13]
	v_add_co_u32_e32 v10, vcc, s27, v10
	s_ashr_i32 s17, s16, 31
	s_and_b32 s46, s18, 0xffffffe0
	v_addc_co_u32_e32 v11, vcc, 0, v11, vcc
	flat_load_dwordx4 v[16:19], v[2:3]
	flat_load_dword v44, v[10:11]
	flat_load_dword v47, v[12:13] offset:256
	flat_load_dwordx4 v[20:23], v[0:1]
	flat_load_dwordx4 v[24:27], v[6:7] offset:64
	flat_load_dwordx4 v[28:31], v[6:7] offset:128
	flat_load_dwordx4 v[32:35], v[6:7] offset:192
	v_lshlrev_b32_e32 v0, 2, v48
	s_lshl_b64 s[22:23], s[16:17], 11
	s_ashr_i32 s16, s46, 31
	v_lshl_or_b32 v0, s8, 6, v0
	v_mov_b32_e32 v1, v41
	s_add_u32 s17, s22, s46
	v_lshl_add_u64 v[0:1], s[34:35], 0, v[0:1]
	v_or_b32_e32 v2, s17, v45
	flat_load_dword v57, v[0:1]
	s_addc_u32 s19, s23, s16
	v_mad_u64_u32 v[0:1], s[16:17], v2, s29, v[42:43]
	v_mad_i32_i24 v1, s19, v56, v1
	s_lshl_b32 s8, s8, 5
	v_lshl_add_u64 v[0:1], v[0:1], 0, s[8:9]
	v_lshl_add_u64 v[0:1], v[0:1], 0, v[40:41]
	v_add_co_u32_e32 v0, vcc, s30, v0
	s_mulk_i32 s19, 0x3800
	s_nop 0
	v_addc_co_u32_e32 v1, vcc, 0, v1, vcc
	s_waitcnt vmcnt(0) lgkmcnt(0)
	flat_load_dwordx4 v[36:39], v[0:1] offset:3072
	v_mad_u64_u32 v[0:1], s[16:17], v2, s29, 0
	s_lshl_b32 s16, s21, 7
	s_add_i32 s47, s16, 0
	s_cmp_lt_u32 s20, 64
	s_cselect_b64 s[16:17], -1, 0
	s_cmp_gt_i32 s45, 3
	v_add_u32_e32 v1, s19, v1
	v_mov_b32_e32 v2, s18
	s_cselect_b64 s[18:19], -1, 0
	s_add_u32 s24, s1, s8
	s_addc_u32 s25, s0, 0
	s_cmp_eq_u32 s21, 0
	s_cselect_b64 s[20:21], -1, 0
	s_lshl_b32 s8, s45, 4
	v_bfi_b32 v58, s28, v2, v14
	s_sub_i32 s8, s8, 64
	v_lshrrev_b32_e32 v2, 2, v14
	v_and_b32_e32 v3, 12, v2
	v_or_b32_e32 v5, s8, v48
	v_or_b32_e32 v62, s8, v3
	v_mul_lo_u32 v5, v5, s36
	s_add_u32 s8, s22, s8
	s_waitcnt lgkmcnt(0)
	s_barrier
	v_lshl_or_b32 v7, v46, 2, s46
	v_lshlrev_b32_e32 v2, 1, v48
	v_add3_u32 v64, s33, v5, v4
	s_addc_u32 s22, s23, 0
	v_or_b32_e32 v4, s8, v3
	v_mov_b32_e32 v3, v41
	v_lshlrev_b32_e32 v6, 2, v45
	v_add_u32_e32 v63, s31, v2
	v_mov_b32_e32 v5, s22
	v_lshl_add_u64 v[48:49], s[24:25], 0, v[2:3]
	v_mul_lo_u32 v2, v7, s37
	v_or3_b32 v0, v0, s44, v40
	v_add_u32_e32 v59, s31, v40
	v_lshl_add_u32 v60, v15, 3, 0
	v_add_u32_e32 v61, s33, v8
	v_add3_u32 v65, s47, v6, v2
	v_lshlrev_b64 v[50:51], 12, v[4:5]
	v_lshl_add_u64 v[52:53], s[6:7], 0, v[0:1]
	s_movk_i32 s44, 0xff80
	s_mov_b32 s8, -2
	v_mov_b32_e32 v54, 0
	v_mov_b32_e32 v55, v41
	s_waitcnt vmcnt(0) lgkmcnt(0)
	v_mov_b32_e32 v45, v44
	v_xor_b32_e32 v46, 0x80000000, v47
	s_mov_b32 s99, s45
	v_mov_b32_e32 v136, v44
	v_mov_b32_e32 v137, v47
	v_mul_f32_e32 v138, v136, v44
	v_mul_f32_e32 v139, v136, v47
	v_fmac_f32_e32 v138, v137, v46
	v_fmac_f32_e32 v139, v137, v44
	v_mul_f32_e32 v140, v138, v44
	v_mul_f32_e32 v141, v138, v47
	v_fmac_f32_e32 v140, v139, v46
	v_fmac_f32_e32 v141, v139, v44
	v_mul_f32_e32 v142, v140, v44
	v_mul_f32_e32 v143, v140, v47
	v_fmac_f32_e32 v142, v141, v46
	v_fmac_f32_e32 v143, v141, v44
	v_mul_f32_e32 v144, v142, v44
	v_mul_f32_e32 v145, v142, v47
	v_fmac_f32_e32 v144, v143, v46
	v_fmac_f32_e32 v145, v143, v44
	v_mul_f32_e32 v146, v144, v44
	v_mul_f32_e32 v147, v144, v47
	v_fmac_f32_e32 v146, v145, v46
	v_fmac_f32_e32 v147, v145, v44
	v_mul_f32_e32 v148, v146, v44
	v_mul_f32_e32 v149, v146, v47
	v_fmac_f32_e32 v148, v147, v46
	v_fmac_f32_e32 v149, v147, v44
	v_mul_f32_e32 v150, v148, v44
	v_mul_f32_e32 v151, v148, v47
	v_fmac_f32_e32 v150, v149, v46
	v_fmac_f32_e32 v151, v149, v44
	v_mul_f32_e32 v152, v150, v44
	v_mul_f32_e32 v153, v150, v47
	v_fmac_f32_e32 v152, v151, v46
	v_fmac_f32_e32 v153, v151, v44
	v_mul_f32_e32 v154, v152, v44
	v_mul_f32_e32 v155, v152, v47
	v_fmac_f32_e32 v154, v153, v46
	v_fmac_f32_e32 v155, v153, v44
	v_mul_f32_e32 v156, v154, v44
	v_mul_f32_e32 v157, v154, v47
	v_fmac_f32_e32 v156, v155, v46
	v_fmac_f32_e32 v157, v155, v44
	v_mul_f32_e32 v158, v156, v44
	v_mul_f32_e32 v159, v156, v47
	v_fmac_f32_e32 v158, v157, v46
	v_fmac_f32_e32 v159, v157, v44
	v_mul_f32_e32 v160, v158, v44
	v_mul_f32_e32 v161, v158, v47
	v_fmac_f32_e32 v160, v159, v46
	v_fmac_f32_e32 v161, v159, v44
	v_mul_f32_e32 v162, v160, v44
	v_mul_f32_e32 v163, v160, v47
	v_fmac_f32_e32 v162, v161, v46
	v_fmac_f32_e32 v163, v161, v44
	v_mul_f32_e32 v164, v162, v44
	v_mul_f32_e32 v165, v162, v47
	v_fmac_f32_e32 v164, v163, v46
	v_fmac_f32_e32 v165, v163, v44
	v_mul_f32_e32 v166, v164, v44
	v_mul_f32_e32 v167, v164, v47
	v_fmac_f32_e32 v166, v165, v46
	v_fmac_f32_e32 v167, v165, v44
	s_lshl_b32 s100, s99, 9
	s_add_i32 s100, s100, 0x1b800
	v_add_u32_e32 v216, s100, v60
	v_add_u32_e32 v217, 0x1b800, v60
	s_branch .LBB0_1348

; __device__ __forceinline__ unsigned pk2(float lo, float hi) { f32x2_c v = {lo, hi}; return __builtin_bit_cast(unsigned, __builtin_convertvector(v, bf16x2_c)); }
; __device__ __forceinline__ void s5_unit(const Args& A, char* lds, int b, int g) {
;     ...
;         if (wave == 0 && i >= 1 && i <= SEQL / 64) { const float* BU = (const float*)(lds + S5_BU) + ((i - 1) & 1) * (64 * 132); bf16* SS = (bf16*)(lds + S5_SS) + ((i - 1) & 1) * (64 * 136);
; #pragma unroll
;             for (int hb = 0; hb < 2; ++hb) { f32x2_c bv[32];
; #pragma unroll
;                 for (int t = 0; t < 32; ++t) bv[t] = *(const f32x2_c*)(BU + (hb * 32 + t) * 132 + 2 * lane);
;                 const f32x2_c a1 = {ar, ar}, a2 = {-ai, ai}; f32x2_c s2 = {sr, si};
; #pragma unroll
;                 for (int t = 0; t < 32; ++t) { const f32x2_c sw = {s2.y, s2.x}; s2 = a1 * s2 + (a2 * sw + bv[t]);
;                     *(unsigned*)(SS + (hb * 32 + t) * 136 + 2 * lane) = pk2(s2.x, s2.y); }
;                 sr = s2.x; si = s2.y; } }
.LBB0_1353:
	s_cmp_gt_u32 s99, 3
	s_cbranch_scc1 .Ls5p_bar
	s_sub_u32 s100, s45, 1
	s_cmp_lt_u32 s100, 32
	s_cbranch_scc0 .Ls5p_bar
	s_andn2_b32 s22, 1, s45
	s_mul_i32 s23, s22, 0x8400
	s_mul_i32 s100, s99, 0x2100
	s_add_i32 s23, s23, s100
	v_add_u32_e32 v40, s23, v60
	ds_read_b64 v[168:169], v40 offset:0
	ds_read_b64 v[170:171], v40 offset:528
	ds_read_b64 v[172:173], v40 offset:1056
	ds_read_b64 v[174:175], v40 offset:1584
	ds_read_b64 v[176:177], v40 offset:2112
	ds_read_b64 v[178:179], v40 offset:2640
	ds_read_b64 v[180:181], v40 offset:3168
	ds_read_b64 v[182:183], v40 offset:3696
	ds_read_b64 v[184:185], v40 offset:4224
	ds_read_b64 v[186:187], v40 offset:4752
	ds_read_b64 v[188:189], v40 offset:5280
	ds_read_b64 v[190:191], v40 offset:5808
	ds_read_b64 v[192:193], v40 offset:6336
	ds_read_b64 v[194:195], v40 offset:6864
	ds_read_b64 v[196:197], v40 offset:7392
	ds_read_b64 v[198:199], v40 offset:7920
	s_waitcnt lgkmcnt(0)
	v_fmac_f32_e32 v170, v46, v169
	v_fmac_f32_e32 v171, v47, v168
	v_fmac_f32_e32 v170, v44, v168
	v_fmac_f32_e32 v171, v45, v169
	v_fmac_f32_e32 v173, v47, v170
	v_fmac_f32_e32 v172, v46, v171
	v_fmac_f32_e32 v173, v45, v171
	v_fmac_f32_e32 v172, v44, v170
	v_fmac_f32_e32 v174, v46, v173
	v_fmac_f32_e32 v175, v47, v172
	v_fmac_f32_e32 v174, v44, v172
	v_fmac_f32_e32 v175, v45, v173
	v_fmac_f32_e32 v177, v47, v174
	v_fmac_f32_e32 v176, v46, v175
	v_fmac_f32_e32 v177, v45, v175
	v_fmac_f32_e32 v176, v44, v174
	v_fmac_f32_e32 v178, v46, v177
	v_fmac_f32_e32 v179, v47, v176
	v_fmac_f32_e32 v178, v44, v176
	v_fmac_f32_e32 v179, v45, v177
	v_fmac_f32_e32 v181, v47, v178
	v_fmac_f32_e32 v180, v46, v179
	v_fmac_f32_e32 v181, v45, v179
	v_fmac_f32_e32 v180, v44, v178
	v_fmac_f32_e32 v182, v46, v181
	v_fmac_f32_e32 v183, v47, v180
	v_fmac_f32_e32 v182, v44, v180
	v_fmac_f32_e32 v183, v45, v181
	v_fmac_f32_e32 v185, v47, v182
	v_fmac_f32_e32 v184, v46, v183
	v_fmac_f32_e32 v185, v45, v183
	v_fmac_f32_e32 v184, v44, v182
	v_fmac_f32_e32 v186, v46, v185
	v_fmac_f32_e32 v187, v47, v184
	v_fmac_f32_e32 v186, v44, v184
	v_fmac_f32_e32 v187, v45, v185
	v_fmac_f32_e32 v189, v47, v186
	v_fmac_f32_e32 v188, v46, v187
	v_fmac_f32_e32 v189, v45, v187
	v_fmac_f32_e32 v188, v44, v186
	v_fmac_f32_e32 v190, v46, v189
	v_fmac_f32_e32 v191, v47, v188
	v_fmac_f32_e32 v190, v44, v188
	v_fmac_f32_e32 v191, v45, v189
	v_fmac_f32_e32 v193, v47, v190
	v_fmac_f32_e32 v192, v46, v191
	v_fmac_f32_e32 v193, v45, v191
	v_fmac_f32_e32 v192, v44, v190
	v_fmac_f32_e32 v194, v46, v193
	v_fmac_f32_e32 v195, v47, v192
	v_fmac_f32_e32 v194, v44, v192
	v_fmac_f32_e32 v195, v45, v193
	v_fmac_f32_e32 v197, v47, v194
	v_fmac_f32_e32 v196, v46, v195
	v_fmac_f32_e32 v197, v45, v195
	v_fmac_f32_e32 v196, v44, v194
	v_fmac_f32_e32 v198, v46, v197
	v_fmac_f32_e32 v199, v47, v196
	v_fmac_f32_e32 v198, v44, v196
	v_fmac_f32_e32 v199, v45, v197
	ds_write_b64 v216, v[198:199]
.Ls5p_bar:
	s_waitcnt lgkmcnt(0)
	s_barrier
	s_cmp_gt_u32 s99, 3
	s_cbranch_scc1 .LBB0_1360
	s_sub_u32 s100, s45, 1
	s_cmp_lt_u32 s100, 32
	s_cbranch_scc0 .LBB0_1360
	ds_read_b64 v[200:201], v217 offset:0
	ds_read_b64 v[202:203], v217 offset:512
	ds_read_b64 v[204:205], v217 offset:1024
	ds_read_b64 v[206:207], v217 offset:1536
	s_andn2_b32 s22, 1, s45
	s_mulk_i32 s22, 0x4400
	s_mul_i32 s100, s99, 0x1100
	s_add_i32 s22, s22, s100
	v_add_u32_e32 v114, s22, v61
	s_waitcnt lgkmcnt(0)
	v_fmac_f32_e32 v200, v166, v54
	v_fmac_f32_e32 v201, v166, v55
	v_fma_f32 v200, -v167, v55, v200
	v_fmac_f32_e32 v201, v167, v54
	v_fmac_f32_e32 v202, v166, v200
	v_fmac_f32_e32 v203, v166, v201
	v_fma_f32 v202, -v167, v201, v202
	v_fmac_f32_e32 v203, v167, v200
	v_fmac_f32_e32 v204, v166, v202
	v_fmac_f32_e32 v205, v166, v203
	v_fma_f32 v204, -v167, v203, v204
	v_fmac_f32_e32 v205, v167, v202
	v_fmac_f32_e32 v206, v166, v204
	v_fmac_f32_e32 v207, v166, v205
	v_fma_f32 v206, -v167, v205, v206
	v_fmac_f32_e32 v207, v167, v204
	v_mov_b32_e32 v208, v54
	v_mov_b32_e32 v209, v55
	s_cmp_eq_u32 s99, 0
	s_cbranch_scc1 .Ls5p_sel
	v_mov_b32_e32 v208, v200
	v_mov_b32_e32 v209, v201
	s_cmp_eq_u32 s99, 1
	s_cbranch_scc1 .Ls5p_sel
	v_mov_b32_e32 v208, v202
	v_mov_b32_e32 v209, v203
	s_cmp_eq_u32 s99, 2
	s_cbranch_scc1 .Ls5p_sel
	v_mov_b32_e32 v208, v204
	v_mov_b32_e32 v209, v205
; __device__ __forceinline__ unsigned pk2(float lo, float hi) { f32x2_c v = {lo, hi}; return __builtin_bit_cast(unsigned, __builtin_convertvector(v, bf16x2_c)); }
; __device__ __forceinline__ void s5_unit(const Args& A, char* lds, int b, int g) {
;     ...
;         if (wave == 0 && i >= 1 && i <= SEQL / 64) { const float* BU = (const float*)(lds + S5_BU) + ((i - 1) & 1) * (64 * 132); bf16* SS = (bf16*)(lds + S5_SS) + ((i - 1) & 1) * (64 * 136);
; #pragma unroll
;             for (int hb = 0; hb < 2; ++hb) { f32x2_c bv[32];
; #pragma unroll
;                 for (int t = 0; t < 32; ++t) bv[t] = *(const f32x2_c*)(BU + (hb * 32 + t) * 132 + 2 * lane);
;                 const f32x2_c a1 = {ar, ar}, a2 = {-ai, ai}; f32x2_c s2 = {sr, si};
; #pragma unroll
;                 for (int t = 0; t < 32; ++t) { const f32x2_c sw = {s2.y, s2.x}; s2 = a1 * s2 + (a2 * sw + bv[t]);
;                     *(unsigned*)(SS + (hb * 32 + t) * 136 + 2 * lane) = pk2(s2.x, s2.y); }
;                 sr = s2.x; si = s2.y; } }
.Ls5p_sel:
	v_mov_b32_e32 v54, v206
	v_mov_b32_e32 v55, v207
	v_fmac_f32_e32 v168, v136, v208
	v_fmac_f32_e32 v169, v136, v209
	v_fma_f32 v168, -v137, v209, v168
	v_fmac_f32_e32 v169, v137, v208
	v_fmac_f32_e32 v170, v138, v208
	v_fmac_f32_e32 v171, v138, v209
	v_fma_f32 v170, -v139, v209, v170
	v_fmac_f32_e32 v171, v139, v208
	v_cvt_pk_bf16_f32 v168, v168, v169
	ds_write_b32 v114, v168 offset:0
	v_fmac_f32_e32 v172, v140, v208
	v_fmac_f32_e32 v173, v140, v209
	v_fma_f32 v172, -v141, v209, v172
	v_fmac_f32_e32 v173, v141, v208
	v_cvt_pk_bf16_f32 v170, v170, v171
	ds_write_b32 v114, v170 offset:272
	v_fmac_f32_e32 v174, v142, v208
	v_fmac_f32_e32 v175, v142, v209
	v_fma_f32 v174, -v143, v209, v174
	v_fmac_f32_e32 v175, v143, v208
	v_cvt_pk_bf16_f32 v172, v172, v173
	ds_write_b32 v114, v172 offset:544
	v_fmac_f32_e32 v176, v144, v208
	v_fmac_f32_e32 v177, v144, v209
	v_fma_f32 v176, -v145, v209, v176
	v_fmac_f32_e32 v177, v145, v208
	v_cvt_pk_bf16_f32 v174, v174, v175
	ds_write_b32 v114, v174 offset:816
	v_fmac_f32_e32 v178, v146, v208
	v_fmac_f32_e32 v179, v146, v209
	v_fma_f32 v178, -v147, v209, v178
	v_fmac_f32_e32 v179, v147, v208
	v_cvt_pk_bf16_f32 v176, v176, v177
	ds_write_b32 v114, v176 offset:1088
	v_fmac_f32_e32 v180, v148, v208
	v_fmac_f32_e32 v181, v148, v209
	v_fma_f32 v180, -v149, v209, v180
	v_fmac_f32_e32 v181, v149, v208
	v_cvt_pk_bf16_f32 v178, v178, v179
	ds_write_b32 v114, v178 offset:1360
	v_fmac_f32_e32 v182, v150, v208
	v_fmac_f32_e32 v183, v150, v209
	v_fma_f32 v182, -v151, v209, v182
	v_fmac_f32_e32 v183, v151, v208
	v_cvt_pk_bf16_f32 v180, v180, v181
	ds_write_b32 v114, v180 offset:1632
	v_fmac_f32_e32 v184, v152, v208
	v_fmac_f32_e32 v185, v152, v209
	v_fma_f32 v184, -v153, v209, v184
	v_fmac_f32_e32 v185, v153, v208
	v_cvt_pk_bf16_f32 v182, v182, v183
	ds_write_b32 v114, v182 offset:1904
	v_fmac_f32_e32 v186, v154, v208
	v_fmac_f32_e32 v187, v154, v209
	v_fma_f32 v186, -v155, v209, v186
	v_fmac_f32_e32 v187, v155, v208
	v_cvt_pk_bf16_f32 v184, v184, v185
	ds_write_b32 v114, v184 offset:2176
	v_fmac_f32_e32 v188, v156, v208
	v_fmac_f32_e32 v189, v156, v209
	v_fma_f32 v188, -v157, v209, v188
	v_fmac_f32_e32 v189, v157, v208
	v_cvt_pk_bf16_f32 v186, v186, v187
	ds_write_b32 v114, v186 offset:2448
	v_fmac_f32_e32 v190, v158, v208
	v_fmac_f32_e32 v191, v158, v209
	v_fma_f32 v190, -v159, v209, v190
	v_fmac_f32_e32 v191, v159, v208
	v_cvt_pk_bf16_f32 v188, v188, v189
	ds_write_b32 v114, v188 offset:2720
	v_fmac_f32_e32 v192, v160, v208
	v_fmac_f32_e32 v193, v160, v209
	v_fma_f32 v192, -v161, v209, v192
	v_fmac_f32_e32 v193, v161, v208
	v_cvt_pk_bf16_f32 v190, v190, v191
	ds_write_b32 v114, v190 offset:2992
	v_fmac_f32_e32 v194, v162, v208
	v_fmac_f32_e32 v195, v162, v209
	v_fma_f32 v194, -v163, v209, v194
	v_fmac_f32_e32 v195, v163, v208
	v_cvt_pk_bf16_f32 v192, v192, v193
	ds_write_b32 v114, v192 offset:3264
	v_fmac_f32_e32 v196, v164, v208
	v_fmac_f32_e32 v197, v164, v209
	v_fma_f32 v196, -v165, v209, v196
	v_fmac_f32_e32 v197, v165, v208
	v_cvt_pk_bf16_f32 v194, v194, v195
	ds_write_b32 v114, v194 offset:3536
	v_fmac_f32_e32 v198, v166, v208
	v_fmac_f32_e32 v199, v166, v209
	v_fma_f32 v198, -v167, v209, v198
	v_fmac_f32_e32 v199, v167, v208
	v_cvt_pk_bf16_f32 v196, v196, v197
	ds_write_b32 v114, v196 offset:3808
	v_cvt_pk_bf16_f32 v198, v198, v199
	ds_write_b32 v114, v198 offset:4080
